# attention loop rebuilt: tile loads and S0 row-max interleaved into the QK MFMA stream, V fragments prefetched before the rescale check, cross-half max by permlane32_swap, scalar adds for row sums
# speedup vs baseline: 1.0383x; 1.0075x over previous
.LBB0_1313:
	s_and_b32 s89, s85, 1
	s_add_i32 s33, s52, 1
	s_cmp_lg_u32 s52, 2
	s_mov_b32 s86, s52
	s_cselect_b32 s52, s33, 0
	s_add_i32 s85, s85, 1
	s_cmp_ge_u32 s85, s53
	s_cselect_b32 s96, 0, 1
	s_cmp_eq_u64 s[10:11], 0
	s_cselect_b32 s97, s96, 0
	s_cmp_eq_u64 s[16:17], 0
	s_cselect_b32 s99, s96, 0
	s_xor_b32 s90, s89, 1
	s_mulk_i32 s90, 0x6400
	s_mul_i32 s91, s52, 0x4800
	s_add_i32 s91, s91, 0xc800
	s_mulk_i32 s89, 0x6400
	s_sub_i32 s33, s84, 63
	s_waitcnt vmcnt(0)
	s_barrier
	s_cmp_gt_u32 s33, s54
	s_cbranch_scc1 .Lfa_noqk
	v_add3_u32 v144, v215, s89, v201
	ds_read_b128 v[168:171], v144
	ds_read_b128 v[172:175], v144 offset:32
	ds_read_b128 v[176:179], v144 offset:64
	ds_read_b128 v[180:183], v144 offset:96
	v_xor_b32_e32 v64, 0x80000000, v242
	v_mov_b32_e32 v65, v64
	v_mov_b32_e32 v66, v64
	v_mov_b32_e32 v67, v64
	v_mov_b32_e32 v68, v64
	v_mov_b32_e32 v69, v64
	v_mov_b32_e32 v70, v64
	v_mov_b32_e32 v71, v64
	v_mov_b32_e32 v72, v64
	v_mov_b32_e32 v73, v64
	v_mov_b32_e32 v74, v64
	v_mov_b32_e32 v75, v64
	v_mov_b32_e32 v76, v64
	v_mov_b32_e32 v77, v64
	v_mov_b32_e32 v78, v64
	v_mov_b32_e32 v79, v64
	s_nop 1
	s_waitcnt lgkmcnt(3)
	v_mfma_f32_32x32x16_bf16 v[80:95], v[168:171], v[96:99], v[64:79]
	ds_read_b128 v[168:171], v144 offset:128
	s_waitcnt lgkmcnt(3)
	v_mfma_f32_32x32x16_bf16 v[80:95], v[172:175], v[100:103], v[80:95]
	ds_read_b128 v[172:175], v144 offset:160
	s_cmp_lg_u32 s96, 0
	s_cbranch_scc0 .Lfa_ls1
	s_add_i32 m0, s90, s51
	s_nop 0
	global_load_lds_dwordx4 v160, s[92:93]
.Lfa_ls1:
	s_waitcnt lgkmcnt(3)
	v_mfma_f32_32x32x16_bf16 v[80:95], v[176:179], v[104:107], v[80:95]
	ds_read_b128 v[176:179], v144 offset:192
	s_waitcnt lgkmcnt(3)
	v_mfma_f32_32x32x16_bf16 v[80:95], v[180:183], v[108:111], v[80:95]
	ds_read_b128 v[180:183], v144 offset:224
	s_waitcnt lgkmcnt(3)
	v_mfma_f32_32x32x16_bf16 v[80:95], v[168:171], v[112:115], v[80:95]
	ds_read_b128 v[168:171], v144 offset:256
	s_cmp_lg_u32 s96, 0
	s_cbranch_scc0 .Lfa_ls2
	s_add_i32 m0, s90, s55
	s_nop 0
	global_load_lds_dwordx4 v162, s[92:93]
.Lfa_ls2:
	s_waitcnt lgkmcnt(3)
	v_mfma_f32_32x32x16_bf16 v[80:95], v[172:175], v[116:119], v[80:95]
	ds_read_b128 v[172:175], v144 offset:288
	s_waitcnt lgkmcnt(3)
	v_mfma_f32_32x32x16_bf16 v[80:95], v[176:179], v[120:123], v[80:95]
	ds_read_b128 v[176:179], v144 offset:320
	s_waitcnt lgkmcnt(3)
	v_mfma_f32_32x32x16_bf16 v[80:95], v[180:183], v[124:127], v[80:95]
	ds_read_b128 v[180:183], v144 offset:352
	s_cmp_lg_u32 s96, 0
	s_cbranch_scc0 .Lfa_ls3
	s_add_i32 m0, s90, s82
	s_nop 0
	global_load_lds_dwordx4 v164, s[92:93]
.Lfa_ls3:
	s_waitcnt lgkmcnt(3)
	v_mfma_f32_32x32x16_bf16 v[80:95], v[168:171], v[128:131], v[80:95]
	ds_read_b128 v[168:171], v144 offset:12800
	s_waitcnt lgkmcnt(3)
	v_mfma_f32_32x32x16_bf16 v[80:95], v[172:175], v[132:135], v[80:95]
	ds_read_b128 v[172:175], v144 offset:12832
	s_waitcnt lgkmcnt(3)
	v_mfma_f32_32x32x16_bf16 v[80:95], v[176:179], v[136:139], v[80:95]
	ds_read_b128 v[176:179], v144 offset:12864
	s_cmp_lg_u32 s97, 0
	s_cbranch_scc0 .Lfa_ls4
	s_add_i32 m0, s90, 0x6000
	s_nop 0
	global_load_lds_dwordx4 v166, s[92:93]
.Lfa_ls4:
	s_waitcnt lgkmcnt(3)
	v_mfma_f32_32x32x16_bf16 v[80:95], v[180:183], v[140:143], v[80:95]
	ds_read_b128 v[180:183], v144 offset:12896
	s_waitcnt lgkmcnt(3)
	v_mfma_f32_32x32x16_bf16 v[64:79], v[168:171], v[96:99], v[64:79]
	ds_read_b128 v[168:171], v144 offset:12928
	s_waitcnt lgkmcnt(3)
	v_mfma_f32_32x32x16_bf16 v[64:79], v[172:175], v[100:103], v[64:79]
	ds_read_b128 v[172:175], v144 offset:12960
	s_cmp_lg_u32 s96, 0
	s_cbranch_scc0 .Lfa_ls5
	s_add_i32 m0, s91, s51
	s_nop 0
	global_load_lds_dwordx4 v154, s[94:95]
.Lfa_ls5:
	s_waitcnt lgkmcnt(3)
	v_mfma_f32_32x32x16_bf16 v[64:79], v[176:179], v[104:107], v[64:79]
	ds_read_b128 v[176:179], v144 offset:12992
	s_waitcnt lgkmcnt(3)
	v_mfma_f32_32x32x16_bf16 v[64:79], v[180:183], v[108:111], v[64:79]
	ds_read_b128 v[180:183], v144 offset:13024
	s_waitcnt lgkmcnt(3)
	v_mfma_f32_32x32x16_bf16 v[64:79], v[168:171], v[112:115], v[64:79]
	ds_read_b128 v[168:171], v144 offset:13056
	s_cmp_lg_u32 s96, 0
	s_cbranch_scc0 .Lfa_ls6
	s_add_i32 m0, s91, s55
	s_nop 0
	global_load_lds_dwordx4 v156, s[94:95]
.Lfa_ls6:
	v_max_f32_e32 v243, v81, v81
	v_max_f32_e32 v210, v80, v80
	s_waitcnt lgkmcnt(3)
	v_mfma_f32_32x32x16_bf16 v[64:79], v[172:175], v[116:119], v[64:79]
	ds_read_b128 v[172:175], v144 offset:13088
	v_max_f32_e32 v243, v210, v243
	v_max3_f32 v243, v243, v82, v83
	s_waitcnt lgkmcnt(3)
	v_mfma_f32_32x32x16_bf16 v[64:79], v[176:179], v[120:123], v[64:79]
	ds_read_b128 v[176:179], v144 offset:13120
	v_max3_f32 v243, v243, v84, v85
	v_max3_f32 v243, v243, v86, v87
	s_waitcnt lgkmcnt(3)
	v_mfma_f32_32x32x16_bf16 v[64:79], v[180:183], v[124:127], v[64:79]
	ds_read_b128 v[180:183], v144 offset:13152
	s_cmp_lg_u32 s99, 0
	s_cbranch_scc0 .Lfa_ls7
	s_add_i32 m0, s91, s82
	s_nop 0
	global_load_lds_dwordx4 v158, s[94:95]
.Lfa_ls7:
	v_max3_f32 v243, v243, v88, v89
	s_waitcnt lgkmcnt(3)
	v_mfma_f32_32x32x16_bf16 v[64:79], v[168:171], v[128:131], v[64:79]
	v_max3_f32 v243, v243, v90, v91
	v_max3_f32 v243, v243, v92, v93
	s_waitcnt lgkmcnt(2)
	v_mfma_f32_32x32x16_bf16 v[64:79], v[172:175], v[132:135], v[64:79]
	v_max3_f32 v243, v243, v94, v95
	s_waitcnt lgkmcnt(1)
	v_mfma_f32_32x32x16_bf16 v[64:79], v[176:179], v[136:139], v[64:79]
	s_waitcnt lgkmcnt(0)
	v_mfma_f32_32x32x16_bf16 v[64:79], v[180:183], v[140:143], v[64:79]
	s_cmp_le_u32 s84, s48
	s_cbranch_scc1 .Lfa_nodiag
	v_add_u32_e32 v144, s84, v200
	v_subrev_u32_e32 v168, 63, v144
	v_cmp_gt_u32_e32 vcc, v168, v153
	s_nop 1
	v_cndmask_b32_e32 v169, v80, v239, vcc
	v_cmp_lt_u32_e32 vcc, v168, v153
	v_subrev_u32_e32 v168, 61, v144
	s_nop 0
	v_cndmask_b32_e32 v80, v169, v80, vcc
	v_cndmask_b32_e32 v81, v239, v81, vcc
	v_cmp_le_u32_e32 vcc, v168, v153
	v_subrev_u32_e32 v168, 60, v144
	s_nop 0
	v_cndmask_b32_e32 v82, v239, v82, vcc
	v_cmp_le_u32_e32 vcc, v168, v153
	v_subrev_u32_e32 v168, 55, v144
	s_nop 0
	v_cndmask_b32_e32 v83, v239, v83, vcc
	v_cmp_le_u32_e32 vcc, v168, v153
	v_subrev_u32_e32 v168, 54, v144
	s_nop 0
	v_cndmask_b32_e32 v84, v239, v84, vcc
	v_cmp_le_u32_e32 vcc, v168, v153
	v_subrev_u32_e32 v168, 53, v144
	s_nop 0
	v_cndmask_b32_e32 v85, v239, v85, vcc
	v_cmp_le_u32_e32 vcc, v168, v153
	v_subrev_u32_e32 v168, 52, v144
	s_nop 0
	v_cndmask_b32_e32 v86, v239, v86, vcc
	v_cmp_le_u32_e32 vcc, v168, v153
	v_subrev_u32_e32 v168, 47, v144
	s_nop 0
	v_cndmask_b32_e32 v87, v239, v87, vcc
	v_cmp_le_u32_e32 vcc, v168, v153
	v_subrev_u32_e32 v168, 46, v144
	s_nop 0
	v_cndmask_b32_e32 v88, v239, v88, vcc
	v_cmp_le_u32_e32 vcc, v168, v153
	v_subrev_u32_e32 v168, 45, v144
	s_nop 0
	v_cndmask_b32_e32 v89, v239, v89, vcc
	v_cmp_le_u32_e32 vcc, v168, v153
	v_subrev_u32_e32 v168, 44, v144
	s_nop 0
	v_cndmask_b32_e32 v90, v239, v90, vcc
	v_cmp_le_u32_e32 vcc, v168, v153
	v_subrev_u32_e32 v168, 39, v144
	s_nop 0
	v_cndmask_b32_e32 v91, v239, v91, vcc
	v_cmp_le_u32_e32 vcc, v168, v153
	v_subrev_u32_e32 v168, 38, v144
	s_nop 0
	v_cndmask_b32_e32 v92, v239, v92, vcc
	v_cmp_le_u32_e32 vcc, v168, v153
	v_subrev_u32_e32 v168, 37, v144
	s_nop 0
	v_cndmask_b32_e32 v93, v239, v93, vcc
	v_cmp_le_u32_e32 vcc, v168, v153
	v_subrev_u32_e32 v168, 36, v144
	s_nop 0
	v_cndmask_b32_e32 v94, v239, v94, vcc
	v_cmp_le_u32_e32 vcc, v168, v153
	v_subrev_u32_e32 v168, 31, v144
	s_nop 0
	v_cndmask_b32_e32 v95, v239, v95, vcc
	v_cmp_le_u32_e32 vcc, v168, v153
	v_subrev_u32_e32 v168, 30, v144
	s_nop 0
	v_cndmask_b32_e32 v64, v239, v64, vcc
	v_cmp_le_u32_e32 vcc, v168, v153
	v_subrev_u32_e32 v168, 29, v144
	s_nop 0
	v_cndmask_b32_e32 v65, v239, v65, vcc
	v_cmp_le_u32_e32 vcc, v168, v153
	v_subrev_u32_e32 v168, 28, v144
	s_nop 0
	v_cndmask_b32_e32 v66, v239, v66, vcc
	v_cmp_le_u32_e32 vcc, v168, v153
	v_subrev_u32_e32 v168, 23, v144
	s_nop 0
	v_cndmask_b32_e32 v67, v239, v67, vcc
	v_cmp_le_u32_e32 vcc, v168, v153
	v_subrev_u32_e32 v168, 22, v144
	s_nop 0
	v_cndmask_b32_e32 v68, v239, v68, vcc
	v_cmp_le_u32_e32 vcc, v168, v153
	v_subrev_u32_e32 v168, 21, v144
	s_nop 0
	v_cndmask_b32_e32 v69, v239, v69, vcc
	v_cmp_le_u32_e32 vcc, v168, v153
	v_subrev_u32_e32 v168, 20, v144
	s_nop 0
	v_cndmask_b32_e32 v70, v239, v70, vcc
	v_cmp_le_u32_e32 vcc, v168, v153
	v_add_u32_e32 v168, -15, v144
	s_nop 0
	v_cndmask_b32_e32 v71, v239, v71, vcc
	v_cmp_le_u32_e32 vcc, v168, v153
	v_add_u32_e32 v168, -14, v144
	s_nop 0
	v_cndmask_b32_e32 v72, v239, v72, vcc
	v_cmp_le_u32_e32 vcc, v168, v153
	v_add_u32_e32 v168, -13, v144
	s_nop 0
	v_cndmask_b32_e32 v73, v239, v73, vcc
	v_cmp_le_u32_e32 vcc, v168, v153
	v_add_u32_e32 v168, -12, v144
	s_nop 0
	v_cndmask_b32_e32 v74, v239, v74, vcc
	v_cmp_le_u32_e32 vcc, v168, v153
	v_add_u32_e32 v168, -7, v144
	s_nop 0
	v_cndmask_b32_e32 v75, v239, v75, vcc
	v_cmp_le_u32_e32 vcc, v168, v153
	v_add_u32_e32 v168, -6, v144
	s_nop 0
	v_cndmask_b32_e32 v76, v239, v76, vcc
	v_cmp_le_u32_e32 vcc, v168, v153
	v_add_u32_e32 v168, -5, v144
	v_add_u32_e32 v144, -4, v144
	v_cndmask_b32_e32 v77, v239, v77, vcc
	v_cmp_le_u32_e32 vcc, v168, v153
	s_nop 1
	v_cndmask_b32_e32 v78, v239, v78, vcc
	v_cmp_le_u32_e32 vcc, v144, v153
	s_nop 1
	v_cndmask_b32_e32 v79, v239, v79, vcc
	v_max_f32_e32 v144, v81, v81
	v_max_f32_e32 v168, v80, v80
	v_max_f32_e32 v144, v168, v144
	v_max3_f32 v144, v144, v82, v83
	v_max3_f32 v144, v144, v84, v85
	v_max3_f32 v144, v144, v86, v87
	v_max3_f32 v144, v144, v88, v89
	v_max3_f32 v144, v144, v90, v91
	v_max3_f32 v144, v144, v92, v93
	v_max3_f32 v144, v144, v94, v95
	s_nop 0
	v_max3_f32 v144, v144, v64, v65
	v_max3_f32 v144, v144, v66, v67
	v_max3_f32 v144, v144, v68, v69
	v_max3_f32 v144, v144, v70, v71
	v_max3_f32 v144, v144, v72, v73
	v_max3_f32 v144, v144, v74, v75
	v_max3_f32 v144, v144, v76, v77
	v_max3_f32 v144, v144, v78, v79
	s_mul_i32 s33, s87, 0x4800
	v_add_u32_e32 v211, s33, v151
	ds_read_b128 v[232:235], v211 offset:51200
	ds_read_b128 v[202:205], v211 offset:55808
	ds_read_b128 v[206:209], v211 offset:60416
	ds_read_b128 v[244:247], v211 offset:65024
	s_branch .Lfa_maxjoin
.Lfa_nodiag:
	s_mul_i32 s33, s87, 0x4800
	v_add_u32_e32 v211, s33, v151
	ds_read_b128 v[232:235], v211 offset:51200
	ds_read_b128 v[202:205], v211 offset:55808
	ds_read_b128 v[206:209], v211 offset:60416
	ds_read_b128 v[244:247], v211 offset:65024
	s_nop 5
	v_max3_f32 v144, v243, v64, v65
	v_max3_f32 v144, v144, v66, v67
	v_max3_f32 v144, v144, v68, v69
	v_max3_f32 v144, v144, v70, v71
	v_max3_f32 v144, v144, v72, v73
	v_max3_f32 v144, v144, v74, v75
	v_max3_f32 v144, v144, v76, v77
	v_max3_f32 v144, v144, v78, v79
.Lfa_maxjoin:
	v_mov_b32_e32 v168, v144
	v_mov_b32_e32 v169, v144
	s_nop 1
	v_permlane32_swap_b32_e32 v168, v169
	v_max_f32_e32 v144, v168, v169
	v_cmp_lt_f32_e32 vcc, s79, v144
	s_cbranch_vccnz .Lfa_rare
	s_waitcnt lgkmcnt(3)
	v_mfma_f32_32x32x16_bf16 v[48:63], v[232:235], v[216:219], v[48:63]
	ds_read_b128 v[232:235], v211 offset:51232
	v_exp_f32_e32 v168, v80
	v_exp_f32_e32 v169, v81
	s_waitcnt lgkmcnt(3)
	v_mfma_f32_32x32x16_bf16 v[32:47], v[202:205], v[216:219], v[32:47]
	ds_read_b128 v[202:205], v211 offset:55840
	v_exp_f32_e32 v170, v82
	v_exp_f32_e32 v171, v83
	v_add_f32_e32 v194, v194, v168
	v_add_f32_e32 v195, v195, v169
	s_waitcnt lgkmcnt(3)
	v_mfma_f32_32x32x16_bf16 v[16:31], v[206:209], v[216:219], v[16:31]
	ds_read_b128 v[206:209], v211 offset:60448
	v_exp_f32_e32 v172, v84
	v_exp_f32_e32 v173, v85
	v_add_f32_e32 v196, v196, v170
	v_add_f32_e32 v197, v197, v171
	s_waitcnt lgkmcnt(3)
	v_mfma_f32_32x32x16_bf16 v[0:15], v[244:247], v[216:219], v[0:15]
	ds_read_b128 v[244:247], v211 offset:65056
	v_exp_f32_e32 v174, v86
	v_exp_f32_e32 v175, v87
	v_add_f32_e32 v194, v194, v172
	v_add_f32_e32 v195, v195, v173
	s_waitcnt lgkmcnt(3)
	v_mfma_f32_32x32x16_bf16 v[48:63], v[232:235], v[220:223], v[48:63]
	ds_read_b128 v[232:235], v211 offset:51264
	v_exp_f32_e32 v176, v88
	v_exp_f32_e32 v177, v89
	v_add_f32_e32 v196, v196, v174
	v_add_f32_e32 v197, v197, v175
	v_cvt_pk_bf16_f32 v216, v168, v169
	s_waitcnt lgkmcnt(3)
	v_mfma_f32_32x32x16_bf16 v[32:47], v[202:205], v[220:223], v[32:47]
	ds_read_b128 v[202:205], v211 offset:55872
	v_exp_f32_e32 v178, v90
	v_exp_f32_e32 v179, v91
	v_add_f32_e32 v194, v194, v176
	v_add_f32_e32 v195, v195, v177
	v_cvt_pk_bf16_f32 v217, v170, v171
	s_waitcnt lgkmcnt(3)
	v_mfma_f32_32x32x16_bf16 v[16:31], v[206:209], v[220:223], v[16:31]
	ds_read_b128 v[206:209], v211 offset:60480
	v_exp_f32_e32 v180, v92
	v_exp_f32_e32 v181, v93
	v_add_f32_e32 v196, v196, v178
	v_add_f32_e32 v197, v197, v179
	v_cvt_pk_bf16_f32 v218, v172, v173
	s_waitcnt lgkmcnt(3)
	v_mfma_f32_32x32x16_bf16 v[0:15], v[244:247], v[220:223], v[0:15]
	ds_read_b128 v[244:247], v211 offset:65088
	v_exp_f32_e32 v182, v94
	v_exp_f32_e32 v183, v95
	v_add_f32_e32 v194, v194, v180
	v_add_f32_e32 v195, v195, v181
	v_cvt_pk_bf16_f32 v219, v174, v175
	s_waitcnt lgkmcnt(3)
	v_mfma_f32_32x32x16_bf16 v[48:63], v[232:235], v[224:227], v[48:63]
	ds_read_b128 v[232:235], v211 offset:51296
	v_exp_f32_e32 v64, v64
	v_exp_f32_e32 v65, v65
	v_add_f32_e32 v196, v196, v182
	v_add_f32_e32 v197, v197, v183
	v_cvt_pk_bf16_f32 v220, v176, v177
	s_waitcnt lgkmcnt(3)
	v_mfma_f32_32x32x16_bf16 v[32:47], v[202:205], v[224:227], v[32:47]
	ds_read_b128 v[202:205], v211 offset:55904
	v_exp_f32_e32 v66, v66
	v_exp_f32_e32 v67, v67
	v_add_f32_e32 v194, v194, v64
	v_add_f32_e32 v195, v195, v65
	v_cvt_pk_bf16_f32 v221, v178, v179
	s_waitcnt lgkmcnt(3)
	v_mfma_f32_32x32x16_bf16 v[16:31], v[206:209], v[224:227], v[16:31]
	ds_read_b128 v[206:209], v211 offset:60512
	v_exp_f32_e32 v68, v68
	v_exp_f32_e32 v69, v69
	v_add_f32_e32 v196, v196, v66
	v_add_f32_e32 v197, v197, v67
	v_cvt_pk_bf16_f32 v222, v180, v181
	s_waitcnt lgkmcnt(3)
	v_mfma_f32_32x32x16_bf16 v[0:15], v[244:247], v[224:227], v[0:15]
	ds_read_b128 v[244:247], v211 offset:65120
	v_exp_f32_e32 v70, v70
	v_exp_f32_e32 v71, v71
	v_add_f32_e32 v194, v194, v68
	v_add_f32_e32 v195, v195, v69
	v_cvt_pk_bf16_f32 v223, v182, v183
	s_waitcnt lgkmcnt(3)
	v_mfma_f32_32x32x16_bf16 v[48:63], v[232:235], v[228:231], v[48:63]
	v_exp_f32_e32 v72, v72
	v_exp_f32_e32 v73, v73
	v_add_f32_e32 v196, v196, v70
	v_add_f32_e32 v197, v197, v71
	v_cvt_pk_bf16_f32 v224, v64, v65
	s_waitcnt lgkmcnt(2)
	v_mfma_f32_32x32x16_bf16 v[32:47], v[202:205], v[228:231], v[32:47]
	v_exp_f32_e32 v74, v74
	v_exp_f32_e32 v75, v75
	v_add_f32_e32 v194, v194, v72
	v_add_f32_e32 v195, v195, v73
	v_cvt_pk_bf16_f32 v225, v66, v67
	s_waitcnt lgkmcnt(1)
	v_mfma_f32_32x32x16_bf16 v[16:31], v[206:209], v[228:231], v[16:31]
	v_exp_f32_e32 v76, v76
	v_exp_f32_e32 v77, v77
	v_add_f32_e32 v196, v196, v74
	v_add_f32_e32 v197, v197, v75
	v_cvt_pk_bf16_f32 v226, v68, v69
	s_waitcnt lgkmcnt(0)
	v_mfma_f32_32x32x16_bf16 v[0:15], v[244:247], v[228:231], v[0:15]
	v_exp_f32_e32 v78, v78
	v_exp_f32_e32 v79, v79
	v_add_f32_e32 v194, v194, v76
	v_add_f32_e32 v195, v195, v77
	v_cvt_pk_bf16_f32 v227, v70, v71
	v_cvt_pk_bf16_f32 v228, v72, v73
	v_add_f32_e32 v196, v196, v78
	v_add_f32_e32 v197, v197, v79
	v_cvt_pk_bf16_f32 v229, v74, v75
	v_cvt_pk_bf16_f32 v230, v76, v77
	v_cvt_pk_bf16_f32 v231, v78, v79
	s_mov_b32 s88, 1
	s_branch .LBB0_1332
.Lfa_rare:
	s_waitcnt lgkmcnt(0)
	s_cmp_eq_u32 s88, 0
	s_cbranch_scc1 .Lfa_rare2
	s_mul_i32 s33, s87, 0x4800
	v_add_u32_e32 v211, s33, v151
	ds_read_b128 v[232:235], v211 offset:51200
	ds_read_b128 v[202:205], v211 offset:55808
	ds_read_b128 v[206:209], v211 offset:60416
	ds_read_b128 v[244:247], v211 offset:65024
	s_waitcnt lgkmcnt(3)
	v_mfma_f32_32x32x16_bf16 v[48:63], v[232:235], v[216:219], v[48:63]
	ds_read_b128 v[232:235], v211 offset:51232
	s_waitcnt lgkmcnt(3)
	v_mfma_f32_32x32x16_bf16 v[32:47], v[202:205], v[216:219], v[32:47]
	ds_read_b128 v[202:205], v211 offset:55840
	s_waitcnt lgkmcnt(3)
	v_mfma_f32_32x32x16_bf16 v[16:31], v[206:209], v[216:219], v[16:31]
	ds_read_b128 v[206:209], v211 offset:60448
	s_waitcnt lgkmcnt(3)
	v_mfma_f32_32x32x16_bf16 v[0:15], v[244:247], v[216:219], v[0:15]
	ds_read_b128 v[244:247], v211 offset:65056
	s_waitcnt lgkmcnt(3)
	v_mfma_f32_32x32x16_bf16 v[48:63], v[232:235], v[220:223], v[48:63]
	ds_read_b128 v[232:235], v211 offset:51264
	s_waitcnt lgkmcnt(3)
	v_mfma_f32_32x32x16_bf16 v[32:47], v[202:205], v[220:223], v[32:47]
	ds_read_b128 v[202:205], v211 offset:55872
	s_waitcnt lgkmcnt(3)
	v_mfma_f32_32x32x16_bf16 v[16:31], v[206:209], v[220:223], v[16:31]
	ds_read_b128 v[206:209], v211 offset:60480
	s_waitcnt lgkmcnt(3)
	v_mfma_f32_32x32x16_bf16 v[0:15], v[244:247], v[220:223], v[0:15]
	ds_read_b128 v[244:247], v211 offset:65088
	s_waitcnt lgkmcnt(3)
	v_mfma_f32_32x32x16_bf16 v[48:63], v[232:235], v[224:227], v[48:63]
	ds_read_b128 v[232:235], v211 offset:51296
	s_waitcnt lgkmcnt(3)
	v_mfma_f32_32x32x16_bf16 v[32:47], v[202:205], v[224:227], v[32:47]
	ds_read_b128 v[202:205], v211 offset:55904
	s_waitcnt lgkmcnt(3)
	v_mfma_f32_32x32x16_bf16 v[16:31], v[206:209], v[224:227], v[16:31]
	ds_read_b128 v[206:209], v211 offset:60512
	s_waitcnt lgkmcnt(3)
	v_mfma_f32_32x32x16_bf16 v[0:15], v[244:247], v[224:227], v[0:15]
	ds_read_b128 v[244:247], v211 offset:65120
	s_waitcnt lgkmcnt(3)
	v_mfma_f32_32x32x16_bf16 v[48:63], v[232:235], v[228:231], v[48:63]
	s_waitcnt lgkmcnt(2)
	v_mfma_f32_32x32x16_bf16 v[32:47], v[202:205], v[228:231], v[32:47]
	s_waitcnt lgkmcnt(1)
	v_mfma_f32_32x32x16_bf16 v[16:31], v[206:209], v[228:231], v[16:31]
	s_waitcnt lgkmcnt(0)
	v_mfma_f32_32x32x16_bf16 v[0:15], v[244:247], v[228:231], v[0:15]

.Lfa_noqk:
	s_cmp_lg_u32 s96, 0
	s_cbranch_scc0 .Lfa_ls8
	s_add_i32 m0, s90, s51
	s_nop 0
	global_load_lds_dwordx4 v160, s[92:93]
.Lfa_ls8:
	s_cmp_lg_u32 s96, 0
	s_cbranch_scc0 .Lfa_ls9
	s_add_i32 m0, s90, s55
	s_nop 0
	global_load_lds_dwordx4 v162, s[92:93]
.Lfa_ls9:
	s_cmp_lg_u32 s96, 0
	s_cbranch_scc0 .Lfa_ls10
	s_add_i32 m0, s90, s82
	s_nop 0
	global_load_lds_dwordx4 v164, s[92:93]
.Lfa_ls10:
	s_cmp_lg_u32 s97, 0
	s_cbranch_scc0 .Lfa_ls11
	s_add_i32 m0, s90, 0x6000
	s_nop 0
	global_load_lds_dwordx4 v166, s[92:93]
.Lfa_ls11:
	s_cmp_lg_u32 s96, 0
	s_cbranch_scc0 .Lfa_ls12
	s_add_i32 m0, s91, s51
	s_nop 0
	global_load_lds_dwordx4 v154, s[94:95]
.Lfa_ls12:
	s_cmp_lg_u32 s96, 0
	s_cbranch_scc0 .Lfa_ls13
	s_add_i32 m0, s91, s55
	s_nop 0
	global_load_lds_dwordx4 v156, s[94:95]
.Lfa_ls13:
	s_cmp_lg_u32 s99, 0
	s_cbranch_scc0 .Lfa_ls14
	s_add_i32 m0, s91, s82
	s_nop 0
	global_load_lds_dwordx4 v158, s[94:95]
.Lfa_ls14:
	s_cmp_eq_u32 s88, 0
	s_cbranch_scc1 .LBB0_1332
	s_mul_i32 s33, s87, 0x4800
	v_add_u32_e32 v211, s33, v151
	ds_read_b128 v[232:235], v211 offset:51200
	ds_read_b128 v[202:205], v211 offset:55808
	ds_read_b128 v[206:209], v211 offset:60416
	ds_read_b128 v[244:247], v211 offset:65024
	s_waitcnt lgkmcnt(3)
	v_mfma_f32_32x32x16_bf16 v[48:63], v[232:235], v[216:219], v[48:63]
	ds_read_b128 v[232:235], v211 offset:51232
	s_waitcnt lgkmcnt(3)
	v_mfma_f32_32x32x16_bf16 v[32:47], v[202:205], v[216:219], v[32:47]
	ds_read_b128 v[202:205], v211 offset:55840
	s_waitcnt lgkmcnt(3)
	v_mfma_f32_32x32x16_bf16 v[16:31], v[206:209], v[216:219], v[16:31]
	ds_read_b128 v[206:209], v211 offset:60448
	s_waitcnt lgkmcnt(3)
	v_mfma_f32_32x32x16_bf16 v[0:15], v[244:247], v[216:219], v[0:15]
	ds_read_b128 v[244:247], v211 offset:65056
	s_waitcnt lgkmcnt(3)
	v_mfma_f32_32x32x16_bf16 v[48:63], v[232:235], v[220:223], v[48:63]
	ds_read_b128 v[232:235], v211 offset:51264
	s_waitcnt lgkmcnt(3)
	v_mfma_f32_32x32x16_bf16 v[32:47], v[202:205], v[220:223], v[32:47]
	ds_read_b128 v[202:205], v211 offset:55872
	s_waitcnt lgkmcnt(3)
	v_mfma_f32_32x32x16_bf16 v[16:31], v[206:209], v[220:223], v[16:31]
	ds_read_b128 v[206:209], v211 offset:60480
	s_waitcnt lgkmcnt(3)
	v_mfma_f32_32x32x16_bf16 v[0:15], v[244:247], v[220:223], v[0:15]
	ds_read_b128 v[244:247], v211 offset:65088
	s_waitcnt lgkmcnt(3)
	v_mfma_f32_32x32x16_bf16 v[48:63], v[232:235], v[224:227], v[48:63]
	ds_read_b128 v[232:235], v211 offset:51296
	s_waitcnt lgkmcnt(3)
	v_mfma_f32_32x32x16_bf16 v[32:47], v[202:205], v[224:227], v[32:47]
	ds_read_b128 v[202:205], v211 offset:55904
	s_waitcnt lgkmcnt(3)
	v_mfma_f32_32x32x16_bf16 v[16:31], v[206:209], v[224:227], v[16:31]
	ds_read_b128 v[206:209], v211 offset:60512
	s_waitcnt lgkmcnt(3)
	v_mfma_f32_32x32x16_bf16 v[0:15], v[244:247], v[224:227], v[0:15]
	ds_read_b128 v[244:247], v211 offset:65120
	s_waitcnt lgkmcnt(3)
	v_mfma_f32_32x32x16_bf16 v[48:63], v[232:235], v[228:231], v[48:63]
	s_waitcnt lgkmcnt(2)
	v_mfma_f32_32x32x16_bf16 v[32:47], v[202:205], v[228:231], v[32:47]
	s_waitcnt lgkmcnt(1)
	v_mfma_f32_32x32x16_bf16 v[16:31], v[206:209], v[228:231], v[16:31]
	s_waitcnt lgkmcnt(0)
	v_mfma_f32_32x32x16_bf16 v[0:15], v[244:247], v[228:231], v[0:15]
	s_mov_b32 s88, 0

.LBB0_1340:
	s_cmp_eq_u32 s88, 0
	s_cbranch_scc1 .Lfa_exit2
	s_mul_i32 s33, s86, 0x4800
	v_add_u32_e32 v211, s33, v151
	ds_read_b128 v[232:235], v211 offset:51200
	ds_read_b128 v[202:205], v211 offset:55808
	ds_read_b128 v[206:209], v211 offset:60416
	ds_read_b128 v[244:247], v211 offset:65024
	s_waitcnt lgkmcnt(3)
	v_mfma_f32_32x32x16_bf16 v[48:63], v[232:235], v[216:219], v[48:63]
	ds_read_b128 v[232:235], v211 offset:51232
	s_waitcnt lgkmcnt(3)
	v_mfma_f32_32x32x16_bf16 v[32:47], v[202:205], v[216:219], v[32:47]
	ds_read_b128 v[202:205], v211 offset:55840
	s_waitcnt lgkmcnt(3)
	v_mfma_f32_32x32x16_bf16 v[16:31], v[206:209], v[216:219], v[16:31]
	ds_read_b128 v[206:209], v211 offset:60448
	s_waitcnt lgkmcnt(3)
	v_mfma_f32_32x32x16_bf16 v[0:15], v[244:247], v[216:219], v[0:15]
	ds_read_b128 v[244:247], v211 offset:65056
	s_waitcnt lgkmcnt(3)
	v_mfma_f32_32x32x16_bf16 v[48:63], v[232:235], v[220:223], v[48:63]
	ds_read_b128 v[232:235], v211 offset:51264
	s_waitcnt lgkmcnt(3)
	v_mfma_f32_32x32x16_bf16 v[32:47], v[202:205], v[220:223], v[32:47]
	ds_read_b128 v[202:205], v211 offset:55872
	s_waitcnt lgkmcnt(3)
	v_mfma_f32_32x32x16_bf16 v[16:31], v[206:209], v[220:223], v[16:31]
	ds_read_b128 v[206:209], v211 offset:60480
	s_waitcnt lgkmcnt(3)
	v_mfma_f32_32x32x16_bf16 v[0:15], v[244:247], v[220:223], v[0:15]
	ds_read_b128 v[244:247], v211 offset:65088
	s_waitcnt lgkmcnt(3)
	v_mfma_f32_32x32x16_bf16 v[48:63], v[232:235], v[224:227], v[48:63]
	ds_read_b128 v[232:235], v211 offset:51296
	s_waitcnt lgkmcnt(3)
	v_mfma_f32_32x32x16_bf16 v[32:47], v[202:205], v[224:227], v[32:47]
	ds_read_b128 v[202:205], v211 offset:55904
	s_waitcnt lgkmcnt(3)
	v_mfma_f32_32x32x16_bf16 v[16:31], v[206:209], v[224:227], v[16:31]
	ds_read_b128 v[206:209], v211 offset:60512
	s_waitcnt lgkmcnt(3)
	v_mfma_f32_32x32x16_bf16 v[0:15], v[244:247], v[224:227], v[0:15]
	ds_read_b128 v[244:247], v211 offset:65120
	s_waitcnt lgkmcnt(3)
	v_mfma_f32_32x32x16_bf16 v[48:63], v[232:235], v[228:231], v[48:63]
	s_waitcnt lgkmcnt(2)
	v_mfma_f32_32x32x16_bf16 v[32:47], v[202:205], v[228:231], v[32:47]
	s_waitcnt lgkmcnt(1)
	v_mfma_f32_32x32x16_bf16 v[16:31], v[206:209], v[228:231], v[16:31]
	s_waitcnt lgkmcnt(0)
	v_mfma_f32_32x32x16_bf16 v[0:15], v[244:247], v[228:231], v[0:15]
